# dilated attention: non-temporal hint on the final y stores only
# speedup vs baseline: 1.0543x; 1.0543x over previous
.LBB0_1735:
	v_div_scale_f32 v0, s[12:13], v3, v3, 1.0
	v_rcp_f32_e32 v2, v0
	v_div_scale_f32 v4, vcc, 1.0, v3, 1.0
	v_fma_f32 v5, -v0, v2, 1.0
	v_fmac_f32_e32 v2, v5, v2
	v_mul_f32_e32 v5, v4, v2
	v_fma_f32 v6, -v0, v5, v4
	v_fmac_f32_e32 v5, v6, v2
	v_fma_f32 v0, -v0, v5, v4
	v_div_fmas_f32 v0, v0, v2, v5
	v_div_fixup_f32 v0, v0, v3, 1.0
	v_pk_mul_f32 v[4:5], v[32:33], v[0:1] op_sel_hi:[1,0]
	v_pk_mul_f32 v[6:7], v[34:35], v[0:1] op_sel_hi:[1,0]
	v_cvt_pk_bf16_f32 v4, v4, v5
	v_cvt_pk_bf16_f32 v5, v6, v7
	v_pk_mul_f32 v[6:7], v[16:17], v[0:1] op_sel_hi:[1,0]
	v_pk_mul_f32 v[8:9], v[18:19], v[0:1] op_sel_hi:[1,0]
	v_lshl_add_u64 v[2:3], v[112:113], 0, v[114:115]
	v_cvt_pk_bf16_f32 v6, v6, v7
	v_cvt_pk_bf16_f32 v7, v8, v9
	global_store_dwordx2 v[2:3], v[4:5], off nt
	global_store_dwordx2 v[2:3], v[6:7], off offset:64 nt
	v_pk_mul_f32 v[4:5], v[36:37], v[0:1] op_sel_hi:[1,0]
	v_pk_mul_f32 v[6:7], v[38:39], v[0:1] op_sel_hi:[1,0]
	v_cvt_pk_bf16_f32 v4, v4, v5
	v_cvt_pk_bf16_f32 v5, v6, v7
	v_pk_mul_f32 v[6:7], v[20:21], v[0:1] op_sel_hi:[1,0]
	v_pk_mul_f32 v[8:9], v[22:23], v[0:1] op_sel_hi:[1,0]
	v_cvt_pk_bf16_f32 v6, v6, v7
	v_cvt_pk_bf16_f32 v7, v8, v9
	global_store_dwordx2 v[2:3], v[4:5], off offset:16 nt
	global_store_dwordx2 v[2:3], v[6:7], off offset:80 nt
	v_pk_mul_f32 v[4:5], v[40:41], v[0:1] op_sel_hi:[1,0]
	v_pk_mul_f32 v[6:7], v[42:43], v[0:1] op_sel_hi:[1,0]
	v_cvt_pk_bf16_f32 v4, v4, v5
	v_cvt_pk_bf16_f32 v5, v6, v7
	v_pk_mul_f32 v[6:7], v[24:25], v[0:1] op_sel_hi:[1,0]
	v_pk_mul_f32 v[8:9], v[26:27], v[0:1] op_sel_hi:[1,0]
	v_cvt_pk_bf16_f32 v6, v6, v7
	v_cvt_pk_bf16_f32 v7, v8, v9
	global_store_dwordx2 v[2:3], v[4:5], off offset:32 nt
	global_store_dwordx2 v[2:3], v[6:7], off offset:96 nt
	v_pk_mul_f32 v[4:5], v[44:45], v[0:1] op_sel_hi:[1,0]
	v_pk_mul_f32 v[6:7], v[46:47], v[0:1] op_sel_hi:[1,0]
	v_cvt_pk_bf16_f32 v4, v4, v5
	v_cvt_pk_bf16_f32 v5, v6, v7
	v_pk_mul_f32 v[6:7], v[28:29], v[0:1] op_sel_hi:[1,0]
	v_pk_mul_f32 v[8:9], v[30:31], v[0:1] op_sel_hi:[1,0]
	v_cvt_pk_bf16_f32 v6, v6, v7
	v_cvt_pk_bf16_f32 v7, v8, v9
	global_store_dwordx2 v[2:3], v[4:5], off offset:48 nt
	global_store_dwordx2 v[2:3], v[6:7], off offset:112 nt
	s_branch .LBB0_1685

.LBB0_3836:
	v_div_scale_f32 v0, s[10:11], v3, v3, 1.0
	v_rcp_f32_e32 v2, v0
	v_div_scale_f32 v4, vcc, 1.0, v3, 1.0
	v_fma_f32 v5, -v0, v2, 1.0
	v_fmac_f32_e32 v2, v5, v2
	v_mul_f32_e32 v5, v4, v2
	v_fma_f32 v6, -v0, v5, v4
	v_fmac_f32_e32 v5, v6, v2
	v_fma_f32 v0, -v0, v5, v4
	v_div_fmas_f32 v0, v0, v2, v5
	v_div_fixup_f32 v0, v0, v3, 1.0
	v_pk_mul_f32 v[4:5], v[32:33], v[0:1] op_sel_hi:[1,0]
	v_pk_mul_f32 v[6:7], v[34:35], v[0:1] op_sel_hi:[1,0]
	v_cvt_pk_bf16_f32 v4, v4, v5
	v_cvt_pk_bf16_f32 v5, v6, v7
	v_pk_mul_f32 v[6:7], v[16:17], v[0:1] op_sel_hi:[1,0]
	v_pk_mul_f32 v[8:9], v[18:19], v[0:1] op_sel_hi:[1,0]
	v_lshl_add_u64 v[2:3], v[112:113], 0, v[114:115]
	v_cvt_pk_bf16_f32 v6, v6, v7
	v_cvt_pk_bf16_f32 v7, v8, v9
	global_store_dwordx2 v[2:3], v[4:5], off nt
	global_store_dwordx2 v[2:3], v[6:7], off offset:64 nt
	v_pk_mul_f32 v[4:5], v[36:37], v[0:1] op_sel_hi:[1,0]
	v_pk_mul_f32 v[6:7], v[38:39], v[0:1] op_sel_hi:[1,0]
	v_cvt_pk_bf16_f32 v4, v4, v5
	v_cvt_pk_bf16_f32 v5, v6, v7
	v_pk_mul_f32 v[6:7], v[20:21], v[0:1] op_sel_hi:[1,0]
	v_pk_mul_f32 v[8:9], v[22:23], v[0:1] op_sel_hi:[1,0]
	v_cvt_pk_bf16_f32 v6, v6, v7
	v_cvt_pk_bf16_f32 v7, v8, v9
	global_store_dwordx2 v[2:3], v[4:5], off offset:16 nt
	global_store_dwordx2 v[2:3], v[6:7], off offset:80 nt
	v_pk_mul_f32 v[4:5], v[40:41], v[0:1] op_sel_hi:[1,0]
	v_pk_mul_f32 v[6:7], v[42:43], v[0:1] op_sel_hi:[1,0]
	v_cvt_pk_bf16_f32 v4, v4, v5
	v_cvt_pk_bf16_f32 v5, v6, v7
	v_pk_mul_f32 v[6:7], v[24:25], v[0:1] op_sel_hi:[1,0]
	v_pk_mul_f32 v[8:9], v[26:27], v[0:1] op_sel_hi:[1,0]
	v_cvt_pk_bf16_f32 v6, v6, v7
	v_cvt_pk_bf16_f32 v7, v8, v9
	global_store_dwordx2 v[2:3], v[4:5], off offset:32 nt
	global_store_dwordx2 v[2:3], v[6:7], off offset:96 nt
	v_pk_mul_f32 v[4:5], v[44:45], v[0:1] op_sel_hi:[1,0]
	v_pk_mul_f32 v[6:7], v[46:47], v[0:1] op_sel_hi:[1,0]
	v_cvt_pk_bf16_f32 v4, v4, v5
	v_cvt_pk_bf16_f32 v5, v6, v7
	v_pk_mul_f32 v[6:7], v[28:29], v[0:1] op_sel_hi:[1,0]
	v_pk_mul_f32 v[8:9], v[30:31], v[0:1] op_sel_hi:[1,0]
	v_cvt_pk_bf16_f32 v6, v6, v7
	v_cvt_pk_bf16_f32 v7, v8, v9
	global_store_dwordx2 v[2:3], v[4:5], off offset:48 nt
	global_store_dwordx2 v[2:3], v[6:7], off offset:112 nt
	s_branch .LBB0_3786
